# final norm gain loads hoisted; row_rstd loops of the q / kv projection tiles fully unrolled with every load in flight
# baseline (speedup 1.0000x reference)
; DI void row_rstd(const u16* Z, int row0, int col0, int ncol, float* rs) {
;     ...
;   for (int i = 0; i < per; i += 8) {
;     u32x4 v = *(const u32x4*)(src + i);
;     unsigned vv[4] = {v.x, v.y, v.z, v.w};
; #pragma unroll
;     for (int q = 0; q < 4; ++q) {
;       float a = __uint_as_float(vv[q] << 16), b = __uint_as_float(vv[q] & 0xffff0000u);
;       s += a * a + b * b;
;     }
;   }
.LBB0_712:
	global_load_dwordx4 v[92:95], v[2:3], off
	global_load_dwordx4 v[96:99], v[2:3], off offset:-16
	global_load_dwordx4 v[100:103], v[2:3], off offset:-32
	global_load_dwordx4 v[104:107], v[2:3], off offset:-48
	v_lshl_add_u64 v[108:109], v[2:3], 0, 64
	global_load_dwordx4 v[112:115], v[108:109], off
	global_load_dwordx4 v[116:119], v[108:109], off offset:-16
	global_load_dwordx4 v[120:123], v[108:109], off offset:-32
	global_load_dwordx4 v[124:127], v[108:109], off offset:-48
	v_lshl_add_u64 v[110:111], v[108:109], 0, 64
	global_load_dwordx4 v[128:131], v[110:111], off
	global_load_dwordx4 v[132:135], v[110:111], off offset:-16
	global_load_dwordx4 v[136:139], v[110:111], off offset:-32
	global_load_dwordx4 v[140:143], v[110:111], off offset:-48
	v_lshl_add_u64 v[144:145], v[110:111], 0, 64
	global_load_dwordx4 v[148:151], v[144:145], off
	global_load_dwordx4 v[152:155], v[144:145], off offset:-16
	global_load_dwordx4 v[156:159], v[144:145], off offset:-32
	global_load_dwordx4 v[160:163], v[144:145], off offset:-48
	s_waitcnt vmcnt(0)
	v_lshlrev_b32_e32 v24, 16, v104
	v_and_b32_e32 v25, 0xffff0000, v104
	v_pk_mul_f32 v[24:25], v[24:25], v[24:25]
	s_nop 0
	v_add_f32_e32 v7, v24, v25
	v_and_b32_e32 v25, 0xffff0000, v106
	v_and_b32_e32 v24, 0xffff0000, v105
	v_add_f32_e32 v26, v6, v7
	v_lshlrev_b32_e32 v7, 16, v106
	v_lshlrev_b32_e32 v6, 16, v105
	v_pk_mul_f32 v[20:21], v[24:25], v[24:25]
	s_nop 0
	v_pk_fma_f32 v[6:7], v[6:7], v[6:7], v[20:21]
	v_and_b32_e32 v21, 0xffff0000, v102
	v_add_f32_e32 v6, v6, v26
	v_add_f32_e32 v20, v7, v6
	v_lshlrev_b32_e32 v6, 16, v107
	v_and_b32_e32 v7, 0xffff0000, v107
	v_pk_mul_f32 v[6:7], v[6:7], v[6:7]
	s_nop 0
	v_add_f32_e32 v6, v6, v7
	v_add_f32_e32 v20, v6, v20
	v_lshlrev_b32_e32 v6, 16, v100
	v_and_b32_e32 v7, 0xffff0000, v100
	v_pk_mul_f32 v[6:7], v[6:7], v[6:7]
	s_nop 0
	v_add_f32_e32 v6, v6, v7
	v_add_f32_e32 v22, v20, v6
	v_and_b32_e32 v20, 0xffff0000, v101
	v_lshlrev_b32_e32 v7, 16, v102
	v_lshlrev_b32_e32 v6, 16, v101
	v_pk_mul_f32 v[16:17], v[20:21], v[20:21]
	s_nop 0
	v_pk_fma_f32 v[6:7], v[6:7], v[6:7], v[16:17]
	v_and_b32_e32 v17, 0xffff0000, v98
	v_add_f32_e32 v6, v6, v22
	v_add_f32_e32 v16, v7, v6
	v_lshlrev_b32_e32 v6, 16, v103
	v_and_b32_e32 v7, 0xffff0000, v103
	v_pk_mul_f32 v[6:7], v[6:7], v[6:7]
	s_nop 0
	v_add_f32_e32 v6, v6, v7
	v_add_f32_e32 v16, v6, v16
	v_lshlrev_b32_e32 v6, 16, v96
	v_and_b32_e32 v7, 0xffff0000, v96
	v_pk_mul_f32 v[6:7], v[6:7], v[6:7]
	s_nop 0
	v_add_f32_e32 v6, v6, v7
	v_add_f32_e32 v18, v16, v6
	v_and_b32_e32 v16, 0xffff0000, v97
	v_lshlrev_b32_e32 v7, 16, v98
	v_lshlrev_b32_e32 v6, 16, v97
	v_pk_mul_f32 v[12:13], v[16:17], v[16:17]
	s_nop 0
	v_pk_fma_f32 v[6:7], v[6:7], v[6:7], v[12:13]
	v_and_b32_e32 v13, 0xffff0000, v94
	v_add_f32_e32 v6, v6, v18
	v_add_f32_e32 v12, v7, v6
	v_lshlrev_b32_e32 v6, 16, v99
	v_and_b32_e32 v7, 0xffff0000, v99
	v_pk_mul_f32 v[6:7], v[6:7], v[6:7]
	s_nop 0
	v_add_f32_e32 v6, v6, v7
	v_add_f32_e32 v12, v6, v12
	v_lshlrev_b32_e32 v6, 16, v92
	v_and_b32_e32 v7, 0xffff0000, v92
	v_pk_mul_f32 v[6:7], v[6:7], v[6:7]
	s_nop 0
	v_add_f32_e32 v6, v6, v7
	v_add_f32_e32 v14, v12, v6
	v_and_b32_e32 v12, 0xffff0000, v93
	v_lshlrev_b32_e32 v7, 16, v94
	v_lshlrev_b32_e32 v6, 16, v93
	v_pk_mul_f32 v[8:9], v[12:13], v[12:13]
	s_nop 0
	v_pk_fma_f32 v[6:7], v[6:7], v[6:7], v[8:9]
	s_nop 0
	v_add_f32_e32 v6, v6, v14
	v_add_f32_e32 v8, v7, v6
	v_lshlrev_b32_e32 v6, 16, v95
	v_and_b32_e32 v7, 0xffff0000, v95
	v_pk_mul_f32 v[6:7], v[6:7], v[6:7]
	s_nop 0
	v_add_f32_e32 v6, v6, v7
	v_add_f32_e32 v6, v6, v8
	v_lshlrev_b32_e32 v24, 16, v124
	v_and_b32_e32 v25, 0xffff0000, v124
	v_pk_mul_f32 v[24:25], v[24:25], v[24:25]
	s_nop 0
	v_add_f32_e32 v7, v24, v25
	v_and_b32_e32 v25, 0xffff0000, v126
	v_and_b32_e32 v24, 0xffff0000, v125
	v_add_f32_e32 v26, v6, v7
	v_lshlrev_b32_e32 v7, 16, v126
	v_lshlrev_b32_e32 v6, 16, v125
	v_pk_mul_f32 v[20:21], v[24:25], v[24:25]
	s_nop 0
	v_pk_fma_f32 v[6:7], v[6:7], v[6:7], v[20:21]
	v_and_b32_e32 v21, 0xffff0000, v122
	v_add_f32_e32 v6, v6, v26
	v_add_f32_e32 v20, v7, v6
	v_lshlrev_b32_e32 v6, 16, v127
	v_and_b32_e32 v7, 0xffff0000, v127
	v_pk_mul_f32 v[6:7], v[6:7], v[6:7]
	s_nop 0
	v_add_f32_e32 v6, v6, v7
	v_add_f32_e32 v20, v6, v20
	v_lshlrev_b32_e32 v6, 16, v120
	v_and_b32_e32 v7, 0xffff0000, v120
	v_pk_mul_f32 v[6:7], v[6:7], v[6:7]
	s_nop 0
	v_add_f32_e32 v6, v6, v7
	v_add_f32_e32 v22, v20, v6
	v_and_b32_e32 v20, 0xffff0000, v121
	v_lshlrev_b32_e32 v7, 16, v122
	v_lshlrev_b32_e32 v6, 16, v121
	v_pk_mul_f32 v[16:17], v[20:21], v[20:21]
	s_nop 0
	v_pk_fma_f32 v[6:7], v[6:7], v[6:7], v[16:17]
	v_and_b32_e32 v17, 0xffff0000, v118
	v_add_f32_e32 v6, v6, v22
	v_add_f32_e32 v16, v7, v6
	v_lshlrev_b32_e32 v6, 16, v123
	v_and_b32_e32 v7, 0xffff0000, v123
	v_pk_mul_f32 v[6:7], v[6:7], v[6:7]
	s_nop 0
	v_add_f32_e32 v6, v6, v7
	v_add_f32_e32 v16, v6, v16
	v_lshlrev_b32_e32 v6, 16, v116
	v_and_b32_e32 v7, 0xffff0000, v116
	v_pk_mul_f32 v[6:7], v[6:7], v[6:7]
	s_nop 0
	v_add_f32_e32 v6, v6, v7
	v_add_f32_e32 v18, v16, v6
	v_and_b32_e32 v16, 0xffff0000, v117
	v_lshlrev_b32_e32 v7, 16, v118
	v_lshlrev_b32_e32 v6, 16, v117
	v_pk_mul_f32 v[12:13], v[16:17], v[16:17]
	s_nop 0
	v_pk_fma_f32 v[6:7], v[6:7], v[6:7], v[12:13]
	v_and_b32_e32 v13, 0xffff0000, v114
	v_add_f32_e32 v6, v6, v18
	v_add_f32_e32 v12, v7, v6
	v_lshlrev_b32_e32 v6, 16, v119
	v_and_b32_e32 v7, 0xffff0000, v119
	v_pk_mul_f32 v[6:7], v[6:7], v[6:7]
	s_nop 0
	v_add_f32_e32 v6, v6, v7
	v_add_f32_e32 v12, v6, v12
	v_lshlrev_b32_e32 v6, 16, v112
	v_and_b32_e32 v7, 0xffff0000, v112
	v_pk_mul_f32 v[6:7], v[6:7], v[6:7]
	s_nop 0
	v_add_f32_e32 v6, v6, v7
; DI void row_rstd(const u16* Z, int row0, int col0, int ncol, float* rs) {
;     ...
;   for (int i = 0; i < per; i += 8) {
;     u32x4 v = *(const u32x4*)(src + i);
;     unsigned vv[4] = {v.x, v.y, v.z, v.w};
; #pragma unroll
;     for (int q = 0; q < 4; ++q) {
;       float a = __uint_as_float(vv[q] << 16), b = __uint_as_float(vv[q] & 0xffff0000u);
;       s += a * a + b * b;
;     }
;   }
;   s += __shfl_xor(s, 1);
;   if (half == 0) rs[rl] = rsqrtf(s / (float)ncol + EPS);
; }
	v_add_f32_e32 v14, v12, v6
	v_and_b32_e32 v12, 0xffff0000, v113
	v_lshlrev_b32_e32 v7, 16, v114
	v_lshlrev_b32_e32 v6, 16, v113
	v_pk_mul_f32 v[8:9], v[12:13], v[12:13]
	s_nop 0
	v_pk_fma_f32 v[6:7], v[6:7], v[6:7], v[8:9]
	s_nop 0
	v_add_f32_e32 v6, v6, v14
	v_add_f32_e32 v8, v7, v6
	v_lshlrev_b32_e32 v6, 16, v115
	v_and_b32_e32 v7, 0xffff0000, v115
	v_pk_mul_f32 v[6:7], v[6:7], v[6:7]
	s_nop 0
	v_add_f32_e32 v6, v6, v7
	v_add_f32_e32 v6, v6, v8
	v_lshlrev_b32_e32 v24, 16, v140
	v_and_b32_e32 v25, 0xffff0000, v140
	v_pk_mul_f32 v[24:25], v[24:25], v[24:25]
	s_nop 0
	v_add_f32_e32 v7, v24, v25
	v_and_b32_e32 v25, 0xffff0000, v142
	v_and_b32_e32 v24, 0xffff0000, v141
	v_add_f32_e32 v26, v6, v7
	v_lshlrev_b32_e32 v7, 16, v142
	v_lshlrev_b32_e32 v6, 16, v141
	v_pk_mul_f32 v[20:21], v[24:25], v[24:25]
	s_nop 0
	v_pk_fma_f32 v[6:7], v[6:7], v[6:7], v[20:21]
	v_and_b32_e32 v21, 0xffff0000, v138
	v_add_f32_e32 v6, v6, v26
	v_add_f32_e32 v20, v7, v6
	v_lshlrev_b32_e32 v6, 16, v143
	v_and_b32_e32 v7, 0xffff0000, v143
	v_pk_mul_f32 v[6:7], v[6:7], v[6:7]
	s_nop 0
	v_add_f32_e32 v6, v6, v7
	v_add_f32_e32 v20, v6, v20
	v_lshlrev_b32_e32 v6, 16, v136
	v_and_b32_e32 v7, 0xffff0000, v136
	v_pk_mul_f32 v[6:7], v[6:7], v[6:7]
	s_nop 0
	v_add_f32_e32 v6, v6, v7
	v_add_f32_e32 v22, v20, v6
	v_and_b32_e32 v20, 0xffff0000, v137
	v_lshlrev_b32_e32 v7, 16, v138
	v_lshlrev_b32_e32 v6, 16, v137
	v_pk_mul_f32 v[16:17], v[20:21], v[20:21]
	s_nop 0
	v_pk_fma_f32 v[6:7], v[6:7], v[6:7], v[16:17]
	v_and_b32_e32 v17, 0xffff0000, v134
	v_add_f32_e32 v6, v6, v22
	v_add_f32_e32 v16, v7, v6
	v_lshlrev_b32_e32 v6, 16, v139
	v_and_b32_e32 v7, 0xffff0000, v139
	v_pk_mul_f32 v[6:7], v[6:7], v[6:7]
	s_nop 0
	v_add_f32_e32 v6, v6, v7
	v_add_f32_e32 v16, v6, v16
	v_lshlrev_b32_e32 v6, 16, v132
	v_and_b32_e32 v7, 0xffff0000, v132
	v_pk_mul_f32 v[6:7], v[6:7], v[6:7]
	s_nop 0
	v_add_f32_e32 v6, v6, v7
	v_add_f32_e32 v18, v16, v6
	v_and_b32_e32 v16, 0xffff0000, v133
	v_lshlrev_b32_e32 v7, 16, v134
	v_lshlrev_b32_e32 v6, 16, v133
	v_pk_mul_f32 v[12:13], v[16:17], v[16:17]
	s_nop 0
	v_pk_fma_f32 v[6:7], v[6:7], v[6:7], v[12:13]
	v_and_b32_e32 v13, 0xffff0000, v130
	v_add_f32_e32 v6, v6, v18
	v_add_f32_e32 v12, v7, v6
	v_lshlrev_b32_e32 v6, 16, v135
	v_and_b32_e32 v7, 0xffff0000, v135
	v_pk_mul_f32 v[6:7], v[6:7], v[6:7]
	s_nop 0
	v_add_f32_e32 v6, v6, v7
	v_add_f32_e32 v12, v6, v12
	v_lshlrev_b32_e32 v6, 16, v128
	v_and_b32_e32 v7, 0xffff0000, v128
	v_pk_mul_f32 v[6:7], v[6:7], v[6:7]
	s_nop 0
	v_add_f32_e32 v6, v6, v7
	v_add_f32_e32 v14, v12, v6
	v_and_b32_e32 v12, 0xffff0000, v129
	v_lshlrev_b32_e32 v7, 16, v130
	v_lshlrev_b32_e32 v6, 16, v129
	v_pk_mul_f32 v[8:9], v[12:13], v[12:13]
	s_nop 0
	v_pk_fma_f32 v[6:7], v[6:7], v[6:7], v[8:9]
	s_nop 0
	v_add_f32_e32 v6, v6, v14
	v_add_f32_e32 v8, v7, v6
	v_lshlrev_b32_e32 v6, 16, v131
	v_and_b32_e32 v7, 0xffff0000, v131
	v_pk_mul_f32 v[6:7], v[6:7], v[6:7]
	s_nop 0
	v_add_f32_e32 v6, v6, v7
	v_add_f32_e32 v6, v6, v8
	v_lshl_add_u64 v[2:3], v[144:145], 0, 64
	v_lshlrev_b32_e32 v24, 16, v160
	v_and_b32_e32 v25, 0xffff0000, v160
	v_pk_mul_f32 v[24:25], v[24:25], v[24:25]
	s_nop 0
	v_add_f32_e32 v7, v24, v25
	v_and_b32_e32 v25, 0xffff0000, v162
	v_and_b32_e32 v24, 0xffff0000, v161
	v_add_f32_e32 v26, v6, v7
	v_lshlrev_b32_e32 v7, 16, v162
	v_lshlrev_b32_e32 v6, 16, v161
	v_pk_mul_f32 v[20:21], v[24:25], v[24:25]
	s_nop 0
	v_pk_fma_f32 v[6:7], v[6:7], v[6:7], v[20:21]
	v_and_b32_e32 v21, 0xffff0000, v158
	v_add_f32_e32 v6, v6, v26
	v_add_f32_e32 v20, v7, v6
	v_lshlrev_b32_e32 v6, 16, v163
	v_and_b32_e32 v7, 0xffff0000, v163
	v_pk_mul_f32 v[6:7], v[6:7], v[6:7]
	s_nop 0
	v_add_f32_e32 v6, v6, v7
	v_add_f32_e32 v20, v6, v20
	v_lshlrev_b32_e32 v6, 16, v156
	v_and_b32_e32 v7, 0xffff0000, v156
	v_pk_mul_f32 v[6:7], v[6:7], v[6:7]
	s_nop 0
	v_add_f32_e32 v6, v6, v7
	v_add_f32_e32 v22, v20, v6
	v_and_b32_e32 v20, 0xffff0000, v157
	v_lshlrev_b32_e32 v7, 16, v158
	v_lshlrev_b32_e32 v6, 16, v157
	v_pk_mul_f32 v[16:17], v[20:21], v[20:21]
	s_nop 0
	v_pk_fma_f32 v[6:7], v[6:7], v[6:7], v[16:17]
	v_and_b32_e32 v17, 0xffff0000, v154
	v_add_f32_e32 v6, v6, v22
	v_add_f32_e32 v16, v7, v6
	v_lshlrev_b32_e32 v6, 16, v159
	v_and_b32_e32 v7, 0xffff0000, v159
	v_pk_mul_f32 v[6:7], v[6:7], v[6:7]
	s_nop 0
	v_add_f32_e32 v6, v6, v7
	v_add_f32_e32 v16, v6, v16
	v_lshlrev_b32_e32 v6, 16, v152
	v_and_b32_e32 v7, 0xffff0000, v152
	v_pk_mul_f32 v[6:7], v[6:7], v[6:7]
	s_nop 0
	v_add_f32_e32 v6, v6, v7
	v_add_f32_e32 v18, v16, v6
	v_and_b32_e32 v16, 0xffff0000, v153
	v_lshlrev_b32_e32 v7, 16, v154
	v_lshlrev_b32_e32 v6, 16, v153
	v_pk_mul_f32 v[12:13], v[16:17], v[16:17]
	s_nop 0
	v_pk_fma_f32 v[6:7], v[6:7], v[6:7], v[12:13]
	v_and_b32_e32 v13, 0xffff0000, v150
	v_add_f32_e32 v6, v6, v18
	v_add_f32_e32 v12, v7, v6
	v_lshlrev_b32_e32 v6, 16, v155
	v_and_b32_e32 v7, 0xffff0000, v155
	v_pk_mul_f32 v[6:7], v[6:7], v[6:7]
	s_nop 0
	v_add_f32_e32 v6, v6, v7
	v_add_f32_e32 v12, v6, v12
	v_lshlrev_b32_e32 v6, 16, v148
	v_and_b32_e32 v7, 0xffff0000, v148
	v_pk_mul_f32 v[6:7], v[6:7], v[6:7]
	s_nop 0
	v_add_f32_e32 v6, v6, v7
	v_add_f32_e32 v14, v12, v6
	v_and_b32_e32 v12, 0xffff0000, v149
	v_lshlrev_b32_e32 v7, 16, v150
	v_lshlrev_b32_e32 v6, 16, v149
	v_pk_mul_f32 v[8:9], v[12:13], v[12:13]
	s_nop 0
	v_pk_fma_f32 v[6:7], v[6:7], v[6:7], v[8:9]
	s_nop 0
	v_add_f32_e32 v6, v6, v14
	v_add_f32_e32 v8, v7, v6
	v_lshlrev_b32_e32 v6, 16, v151
	v_and_b32_e32 v7, 0xffff0000, v151
	v_pk_mul_f32 v[6:7], v[6:7], v[6:7]
	s_nop 0
	v_add_f32_e32 v6, v6, v7
	v_add_f32_e32 v6, v6, v8
	v_and_b32_e32 v3, 64, v219
	v_xor_b32_e32 v2, 1, v219
	v_add_u32_e32 v3, 64, v3
	v_cmp_lt_i32_e32 vcc, v2, v3
	s_nop 1
	v_cndmask_b32_e32 v2, v219, v2, vcc
	v_lshlrev_b32_e32 v2, 2, v2
	ds_bpermute_b32 v2, v2, v6
	v_cmp_eq_u32_e32 vcc, 0, v5
	s_and_saveexec_b64 s[8:9], vcc
	s_cbranch_execz .LBB0_715
	s_waitcnt lgkmcnt(0)
	v_add_f32_e32 v2, v6, v2
	v_mov_b32_e32 v3, 0x358637bd
	v_fmamk_f32 v2, v2, 0x3b800000, v3
	s_mov_b32 s2, 0x800000
	v_mul_f32_e32 v3, 0x4b800000, v2
	v_cmp_gt_f32_e32 vcc, s2, v2
	s_nop 1
	v_cndmask_b32_e32 v2, v2, v3, vcc
	v_rsq_f32_e32 v2, v2
	s_nop 0
	v_mul_f32_e32 v3, 0x45800000, v2
	v_cndmask_b32_e32 v2, v2, v3, vcc
	v_lshl_add_u32 v3, v4, 2, v234
	ds_write_b32 v3, v2

; DI void row_rstd(const u16* Z, int row0, int col0, int ncol, float* rs) {
;     ...
;   for (int i = 0; i < per; i += 8) {
;     u32x4 v = *(const u32x4*)(src + i);
;     unsigned vv[4] = {v.x, v.y, v.z, v.w};
; #pragma unroll
;     for (int q = 0; q < 4; ++q) {
;       float a = __uint_as_float(vv[q] << 16), b = __uint_as_float(vv[q] & 0xffff0000u);
;       s += a * a + b * b;
;     }
;   }
.LBB0_732:
	global_load_dwordx4 v[92:95], v[2:3], off
	global_load_dwordx4 v[96:99], v[2:3], off offset:-16
	global_load_dwordx4 v[100:103], v[2:3], off offset:-32
	global_load_dwordx4 v[104:107], v[2:3], off offset:-48
	v_lshl_add_u64 v[108:109], v[2:3], 0, 64
	global_load_dwordx4 v[112:115], v[108:109], off
	global_load_dwordx4 v[116:119], v[108:109], off offset:-16
	global_load_dwordx4 v[120:123], v[108:109], off offset:-32
	global_load_dwordx4 v[124:127], v[108:109], off offset:-48
	v_lshl_add_u64 v[110:111], v[108:109], 0, 64
	global_load_dwordx4 v[128:131], v[110:111], off
	global_load_dwordx4 v[132:135], v[110:111], off offset:-16
	global_load_dwordx4 v[136:139], v[110:111], off offset:-32
	global_load_dwordx4 v[140:143], v[110:111], off offset:-48
	v_lshl_add_u64 v[144:145], v[110:111], 0, 64
	global_load_dwordx4 v[148:151], v[144:145], off
	global_load_dwordx4 v[152:155], v[144:145], off offset:-16
	global_load_dwordx4 v[156:159], v[144:145], off offset:-32
	global_load_dwordx4 v[160:163], v[144:145], off offset:-48
	v_lshl_add_u64 v[146:147], v[144:145], 0, 64
	global_load_dwordx4 v[164:167], v[146:147], off
	global_load_dwordx4 v[168:171], v[146:147], off offset:-16
	global_load_dwordx4 v[172:175], v[146:147], off offset:-32
	global_load_dwordx4 v[176:179], v[146:147], off offset:-48
	v_lshl_add_u64 v[180:181], v[146:147], 0, 64
	global_load_dwordx4 v[184:187], v[180:181], off
	global_load_dwordx4 v[188:191], v[180:181], off offset:-16
	global_load_dwordx4 v[192:195], v[180:181], off offset:-32
	global_load_dwordx4 v[200:203], v[180:181], off offset:-48
	s_waitcnt vmcnt(0)
	v_lshlrev_b32_e32 v24, 16, v104
	v_and_b32_e32 v25, 0xffff0000, v104
	v_pk_mul_f32 v[24:25], v[24:25], v[24:25]
	s_nop 0
	v_add_f32_e32 v7, v24, v25
	v_and_b32_e32 v25, 0xffff0000, v106
	v_and_b32_e32 v24, 0xffff0000, v105
	v_add_f32_e32 v26, v6, v7
	v_lshlrev_b32_e32 v7, 16, v106
	v_lshlrev_b32_e32 v6, 16, v105
	v_pk_mul_f32 v[20:21], v[24:25], v[24:25]
	s_nop 0
	v_pk_fma_f32 v[6:7], v[6:7], v[6:7], v[20:21]
	v_and_b32_e32 v21, 0xffff0000, v102
	v_add_f32_e32 v6, v6, v26
	v_add_f32_e32 v20, v7, v6
	v_lshlrev_b32_e32 v6, 16, v107
	v_and_b32_e32 v7, 0xffff0000, v107
	v_pk_mul_f32 v[6:7], v[6:7], v[6:7]
	s_nop 0
	v_add_f32_e32 v6, v6, v7
	v_add_f32_e32 v20, v6, v20
	v_lshlrev_b32_e32 v6, 16, v100
	v_and_b32_e32 v7, 0xffff0000, v100
	v_pk_mul_f32 v[6:7], v[6:7], v[6:7]
	s_nop 0
	v_add_f32_e32 v6, v6, v7
	v_add_f32_e32 v22, v20, v6
	v_and_b32_e32 v20, 0xffff0000, v101
	v_lshlrev_b32_e32 v7, 16, v102
	v_lshlrev_b32_e32 v6, 16, v101
	v_pk_mul_f32 v[16:17], v[20:21], v[20:21]
	s_nop 0
	v_pk_fma_f32 v[6:7], v[6:7], v[6:7], v[16:17]
	v_and_b32_e32 v17, 0xffff0000, v98
	v_add_f32_e32 v6, v6, v22
	v_add_f32_e32 v16, v7, v6
	v_lshlrev_b32_e32 v6, 16, v103
	v_and_b32_e32 v7, 0xffff0000, v103
	v_pk_mul_f32 v[6:7], v[6:7], v[6:7]
	s_nop 0
	v_add_f32_e32 v6, v6, v7
	v_add_f32_e32 v16, v6, v16
	v_lshlrev_b32_e32 v6, 16, v96
	v_and_b32_e32 v7, 0xffff0000, v96
	v_pk_mul_f32 v[6:7], v[6:7], v[6:7]
	s_nop 0
	v_add_f32_e32 v6, v6, v7
	v_add_f32_e32 v18, v16, v6
	v_and_b32_e32 v16, 0xffff0000, v97
	v_lshlrev_b32_e32 v7, 16, v98
	v_lshlrev_b32_e32 v6, 16, v97
	v_pk_mul_f32 v[12:13], v[16:17], v[16:17]
	s_nop 0
	v_pk_fma_f32 v[6:7], v[6:7], v[6:7], v[12:13]
	v_and_b32_e32 v13, 0xffff0000, v94
	v_add_f32_e32 v6, v6, v18
	v_add_f32_e32 v12, v7, v6
	v_lshlrev_b32_e32 v6, 16, v99
	v_and_b32_e32 v7, 0xffff0000, v99
	v_pk_mul_f32 v[6:7], v[6:7], v[6:7]
	s_nop 0
	v_add_f32_e32 v6, v6, v7
	v_add_f32_e32 v12, v6, v12
	v_lshlrev_b32_e32 v6, 16, v92
	v_and_b32_e32 v7, 0xffff0000, v92
	v_pk_mul_f32 v[6:7], v[6:7], v[6:7]
	s_nop 0
	v_add_f32_e32 v6, v6, v7
	v_add_f32_e32 v14, v12, v6
	v_and_b32_e32 v12, 0xffff0000, v93
	v_lshlrev_b32_e32 v7, 16, v94
	v_lshlrev_b32_e32 v6, 16, v93
	v_pk_mul_f32 v[8:9], v[12:13], v[12:13]
	s_nop 0
	v_pk_fma_f32 v[6:7], v[6:7], v[6:7], v[8:9]
	s_nop 0
	v_add_f32_e32 v6, v6, v14
	v_add_f32_e32 v8, v7, v6
	v_lshlrev_b32_e32 v6, 16, v95
	v_and_b32_e32 v7, 0xffff0000, v95
	v_pk_mul_f32 v[6:7], v[6:7], v[6:7]
	s_nop 0
	v_add_f32_e32 v6, v6, v7
	v_add_f32_e32 v6, v6, v8
	v_lshlrev_b32_e32 v24, 16, v124
	v_and_b32_e32 v25, 0xffff0000, v124
	v_pk_mul_f32 v[24:25], v[24:25], v[24:25]
	s_nop 0
	v_add_f32_e32 v7, v24, v25
	v_and_b32_e32 v25, 0xffff0000, v126
	v_and_b32_e32 v24, 0xffff0000, v125
	v_add_f32_e32 v26, v6, v7
	v_lshlrev_b32_e32 v7, 16, v126
	v_lshlrev_b32_e32 v6, 16, v125
	v_pk_mul_f32 v[20:21], v[24:25], v[24:25]
	s_nop 0
	v_pk_fma_f32 v[6:7], v[6:7], v[6:7], v[20:21]
	v_and_b32_e32 v21, 0xffff0000, v122
	v_add_f32_e32 v6, v6, v26
	v_add_f32_e32 v20, v7, v6
	v_lshlrev_b32_e32 v6, 16, v127
	v_and_b32_e32 v7, 0xffff0000, v127
	v_pk_mul_f32 v[6:7], v[6:7], v[6:7]
	s_nop 0
	v_add_f32_e32 v6, v6, v7
	v_add_f32_e32 v20, v6, v20
	v_lshlrev_b32_e32 v6, 16, v120
	v_and_b32_e32 v7, 0xffff0000, v120
	v_pk_mul_f32 v[6:7], v[6:7], v[6:7]
	s_nop 0
	v_add_f32_e32 v6, v6, v7
	v_add_f32_e32 v22, v20, v6
	v_and_b32_e32 v20, 0xffff0000, v121
	v_lshlrev_b32_e32 v7, 16, v122
	v_lshlrev_b32_e32 v6, 16, v121
	v_pk_mul_f32 v[16:17], v[20:21], v[20:21]
	s_nop 0
	v_pk_fma_f32 v[6:7], v[6:7], v[6:7], v[16:17]
	v_and_b32_e32 v17, 0xffff0000, v118
	v_add_f32_e32 v6, v6, v22
	v_add_f32_e32 v16, v7, v6
	v_lshlrev_b32_e32 v6, 16, v123
	v_and_b32_e32 v7, 0xffff0000, v123
	v_pk_mul_f32 v[6:7], v[6:7], v[6:7]
	s_nop 0
	v_add_f32_e32 v6, v6, v7
	v_add_f32_e32 v16, v6, v16
	v_lshlrev_b32_e32 v6, 16, v116
	v_and_b32_e32 v7, 0xffff0000, v116
	v_pk_mul_f32 v[6:7], v[6:7], v[6:7]
	s_nop 0
	v_add_f32_e32 v6, v6, v7
	v_add_f32_e32 v18, v16, v6
	v_and_b32_e32 v16, 0xffff0000, v117
	v_lshlrev_b32_e32 v7, 16, v118
; DI void row_rstd(const u16* Z, int row0, int col0, int ncol, float* rs) {
;     ...
;   for (int i = 0; i < per; i += 8) {
;     u32x4 v = *(const u32x4*)(src + i);
;     unsigned vv[4] = {v.x, v.y, v.z, v.w};
; #pragma unroll
;     for (int q = 0; q < 4; ++q) {
;       float a = __uint_as_float(vv[q] << 16), b = __uint_as_float(vv[q] & 0xffff0000u);
;       s += a * a + b * b;
;     }
;   }
	v_lshlrev_b32_e32 v6, 16, v117
	v_pk_mul_f32 v[12:13], v[16:17], v[16:17]
	s_nop 0
	v_pk_fma_f32 v[6:7], v[6:7], v[6:7], v[12:13]
	v_and_b32_e32 v13, 0xffff0000, v114
	v_add_f32_e32 v6, v6, v18
	v_add_f32_e32 v12, v7, v6
	v_lshlrev_b32_e32 v6, 16, v119
	v_and_b32_e32 v7, 0xffff0000, v119
	v_pk_mul_f32 v[6:7], v[6:7], v[6:7]
	s_nop 0
	v_add_f32_e32 v6, v6, v7
	v_add_f32_e32 v12, v6, v12
	v_lshlrev_b32_e32 v6, 16, v112
	v_and_b32_e32 v7, 0xffff0000, v112
	v_pk_mul_f32 v[6:7], v[6:7], v[6:7]
	s_nop 0
	v_add_f32_e32 v6, v6, v7
	v_add_f32_e32 v14, v12, v6
	v_and_b32_e32 v12, 0xffff0000, v113
	v_lshlrev_b32_e32 v7, 16, v114
	v_lshlrev_b32_e32 v6, 16, v113
	v_pk_mul_f32 v[8:9], v[12:13], v[12:13]
	s_nop 0
	v_pk_fma_f32 v[6:7], v[6:7], v[6:7], v[8:9]
	s_nop 0
	v_add_f32_e32 v6, v6, v14
	v_add_f32_e32 v8, v7, v6
	v_lshlrev_b32_e32 v6, 16, v115
	v_and_b32_e32 v7, 0xffff0000, v115
	v_pk_mul_f32 v[6:7], v[6:7], v[6:7]
	s_nop 0
	v_add_f32_e32 v6, v6, v7
	v_add_f32_e32 v6, v6, v8
	v_lshlrev_b32_e32 v24, 16, v140
	v_and_b32_e32 v25, 0xffff0000, v140
	v_pk_mul_f32 v[24:25], v[24:25], v[24:25]
	s_nop 0
	v_add_f32_e32 v7, v24, v25
	v_and_b32_e32 v25, 0xffff0000, v142
	v_and_b32_e32 v24, 0xffff0000, v141
	v_add_f32_e32 v26, v6, v7
	v_lshlrev_b32_e32 v7, 16, v142
	v_lshlrev_b32_e32 v6, 16, v141
	v_pk_mul_f32 v[20:21], v[24:25], v[24:25]
	s_nop 0
	v_pk_fma_f32 v[6:7], v[6:7], v[6:7], v[20:21]
	v_and_b32_e32 v21, 0xffff0000, v138
	v_add_f32_e32 v6, v6, v26
	v_add_f32_e32 v20, v7, v6
	v_lshlrev_b32_e32 v6, 16, v143
	v_and_b32_e32 v7, 0xffff0000, v143
	v_pk_mul_f32 v[6:7], v[6:7], v[6:7]
	s_nop 0
	v_add_f32_e32 v6, v6, v7
	v_add_f32_e32 v20, v6, v20
	v_lshlrev_b32_e32 v6, 16, v136
	v_and_b32_e32 v7, 0xffff0000, v136
	v_pk_mul_f32 v[6:7], v[6:7], v[6:7]
	s_nop 0
	v_add_f32_e32 v6, v6, v7
	v_add_f32_e32 v22, v20, v6
	v_and_b32_e32 v20, 0xffff0000, v137
	v_lshlrev_b32_e32 v7, 16, v138
	v_lshlrev_b32_e32 v6, 16, v137
	v_pk_mul_f32 v[16:17], v[20:21], v[20:21]
	s_nop 0
	v_pk_fma_f32 v[6:7], v[6:7], v[6:7], v[16:17]
	v_and_b32_e32 v17, 0xffff0000, v134
	v_add_f32_e32 v6, v6, v22
	v_add_f32_e32 v16, v7, v6
	v_lshlrev_b32_e32 v6, 16, v139
	v_and_b32_e32 v7, 0xffff0000, v139
	v_pk_mul_f32 v[6:7], v[6:7], v[6:7]
	s_nop 0
	v_add_f32_e32 v6, v6, v7
	v_add_f32_e32 v16, v6, v16
	v_lshlrev_b32_e32 v6, 16, v132
	v_and_b32_e32 v7, 0xffff0000, v132
	v_pk_mul_f32 v[6:7], v[6:7], v[6:7]
	s_nop 0
	v_add_f32_e32 v6, v6, v7
	v_add_f32_e32 v18, v16, v6
	v_and_b32_e32 v16, 0xffff0000, v133
	v_lshlrev_b32_e32 v7, 16, v134
	v_lshlrev_b32_e32 v6, 16, v133
	v_pk_mul_f32 v[12:13], v[16:17], v[16:17]
	s_nop 0
	v_pk_fma_f32 v[6:7], v[6:7], v[6:7], v[12:13]
	v_and_b32_e32 v13, 0xffff0000, v130
	v_add_f32_e32 v6, v6, v18
	v_add_f32_e32 v12, v7, v6
	v_lshlrev_b32_e32 v6, 16, v135
	v_and_b32_e32 v7, 0xffff0000, v135
	v_pk_mul_f32 v[6:7], v[6:7], v[6:7]
	s_nop 0
	v_add_f32_e32 v6, v6, v7
	v_add_f32_e32 v12, v6, v12
	v_lshlrev_b32_e32 v6, 16, v128
	v_and_b32_e32 v7, 0xffff0000, v128
	v_pk_mul_f32 v[6:7], v[6:7], v[6:7]
	s_nop 0
	v_add_f32_e32 v6, v6, v7
	v_add_f32_e32 v14, v12, v6
	v_and_b32_e32 v12, 0xffff0000, v129
	v_lshlrev_b32_e32 v7, 16, v130
	v_lshlrev_b32_e32 v6, 16, v129
	v_pk_mul_f32 v[8:9], v[12:13], v[12:13]
	s_nop 0
	v_pk_fma_f32 v[6:7], v[6:7], v[6:7], v[8:9]
	s_nop 0
	v_add_f32_e32 v6, v6, v14
	v_add_f32_e32 v8, v7, v6
	v_lshlrev_b32_e32 v6, 16, v131
	v_and_b32_e32 v7, 0xffff0000, v131
	v_pk_mul_f32 v[6:7], v[6:7], v[6:7]
	s_nop 0
	v_add_f32_e32 v6, v6, v7
	v_add_f32_e32 v6, v6, v8
	v_lshlrev_b32_e32 v24, 16, v160
	v_and_b32_e32 v25, 0xffff0000, v160
	v_pk_mul_f32 v[24:25], v[24:25], v[24:25]
	s_nop 0
	v_add_f32_e32 v7, v24, v25
	v_and_b32_e32 v25, 0xffff0000, v162
	v_and_b32_e32 v24, 0xffff0000, v161
	v_add_f32_e32 v26, v6, v7
	v_lshlrev_b32_e32 v7, 16, v162
	v_lshlrev_b32_e32 v6, 16, v161
	v_pk_mul_f32 v[20:21], v[24:25], v[24:25]
	s_nop 0
	v_pk_fma_f32 v[6:7], v[6:7], v[6:7], v[20:21]
	v_and_b32_e32 v21, 0xffff0000, v158
	v_add_f32_e32 v6, v6, v26
	v_add_f32_e32 v20, v7, v6
	v_lshlrev_b32_e32 v6, 16, v163
	v_and_b32_e32 v7, 0xffff0000, v163
	v_pk_mul_f32 v[6:7], v[6:7], v[6:7]
	s_nop 0
	v_add_f32_e32 v6, v6, v7
	v_add_f32_e32 v20, v6, v20
	v_lshlrev_b32_e32 v6, 16, v156
	v_and_b32_e32 v7, 0xffff0000, v156
	v_pk_mul_f32 v[6:7], v[6:7], v[6:7]
	s_nop 0
	v_add_f32_e32 v6, v6, v7
	v_add_f32_e32 v22, v20, v6
	v_and_b32_e32 v20, 0xffff0000, v157
	v_lshlrev_b32_e32 v7, 16, v158
	v_lshlrev_b32_e32 v6, 16, v157
	v_pk_mul_f32 v[16:17], v[20:21], v[20:21]
	s_nop 0
	v_pk_fma_f32 v[6:7], v[6:7], v[6:7], v[16:17]
	v_and_b32_e32 v17, 0xffff0000, v154
	v_add_f32_e32 v6, v6, v22
	v_add_f32_e32 v16, v7, v6
	v_lshlrev_b32_e32 v6, 16, v159
	v_and_b32_e32 v7, 0xffff0000, v159
	v_pk_mul_f32 v[6:7], v[6:7], v[6:7]
	s_nop 0
	v_add_f32_e32 v6, v6, v7
	v_add_f32_e32 v16, v6, v16
	v_lshlrev_b32_e32 v6, 16, v152
	v_and_b32_e32 v7, 0xffff0000, v152
	v_pk_mul_f32 v[6:7], v[6:7], v[6:7]
	s_nop 0
	v_add_f32_e32 v6, v6, v7
	v_add_f32_e32 v18, v16, v6
	v_and_b32_e32 v16, 0xffff0000, v153
	v_lshlrev_b32_e32 v7, 16, v154
	v_lshlrev_b32_e32 v6, 16, v153
	v_pk_mul_f32 v[12:13], v[16:17], v[16:17]
	s_nop 0
	v_pk_fma_f32 v[6:7], v[6:7], v[6:7], v[12:13]
	v_and_b32_e32 v13, 0xffff0000, v150
	v_add_f32_e32 v6, v6, v18
	v_add_f32_e32 v12, v7, v6
	v_lshlrev_b32_e32 v6, 16, v155
	v_and_b32_e32 v7, 0xffff0000, v155
	v_pk_mul_f32 v[6:7], v[6:7], v[6:7]
	s_nop 0
	v_add_f32_e32 v6, v6, v7
	v_add_f32_e32 v12, v6, v12
	v_lshlrev_b32_e32 v6, 16, v148
	v_and_b32_e32 v7, 0xffff0000, v148
	v_pk_mul_f32 v[6:7], v[6:7], v[6:7]
	s_nop 0
	v_add_f32_e32 v6, v6, v7
	v_add_f32_e32 v14, v12, v6
	v_and_b32_e32 v12, 0xffff0000, v149
; DI void row_rstd(const u16* Z, int row0, int col0, int ncol, float* rs) {
;     ...
;   for (int i = 0; i < per; i += 8) {
;     u32x4 v = *(const u32x4*)(src + i);
;     unsigned vv[4] = {v.x, v.y, v.z, v.w};
; #pragma unroll
;     for (int q = 0; q < 4; ++q) {
;       float a = __uint_as_float(vv[q] << 16), b = __uint_as_float(vv[q] & 0xffff0000u);
;       s += a * a + b * b;
;     }
;   }
;   s += __shfl_xor(s, 1);
;   if (half == 0) rs[rl] = rsqrtf(s / (float)ncol + EPS);
; }
	v_lshlrev_b32_e32 v7, 16, v150
	v_lshlrev_b32_e32 v6, 16, v149
	v_pk_mul_f32 v[8:9], v[12:13], v[12:13]
	s_nop 0
	v_pk_fma_f32 v[6:7], v[6:7], v[6:7], v[8:9]
	s_nop 0
	v_add_f32_e32 v6, v6, v14
	v_add_f32_e32 v8, v7, v6
	v_lshlrev_b32_e32 v6, 16, v151
	v_and_b32_e32 v7, 0xffff0000, v151
	v_pk_mul_f32 v[6:7], v[6:7], v[6:7]
	s_nop 0
	v_add_f32_e32 v6, v6, v7
	v_add_f32_e32 v6, v6, v8
	v_lshlrev_b32_e32 v24, 16, v176
	v_and_b32_e32 v25, 0xffff0000, v176
	v_pk_mul_f32 v[24:25], v[24:25], v[24:25]
	s_nop 0
	v_add_f32_e32 v7, v24, v25
	v_and_b32_e32 v25, 0xffff0000, v178
	v_and_b32_e32 v24, 0xffff0000, v177
	v_add_f32_e32 v26, v6, v7
	v_lshlrev_b32_e32 v7, 16, v178
	v_lshlrev_b32_e32 v6, 16, v177
	v_pk_mul_f32 v[20:21], v[24:25], v[24:25]
	s_nop 0
	v_pk_fma_f32 v[6:7], v[6:7], v[6:7], v[20:21]
	v_and_b32_e32 v21, 0xffff0000, v174
	v_add_f32_e32 v6, v6, v26
	v_add_f32_e32 v20, v7, v6
	v_lshlrev_b32_e32 v6, 16, v179
	v_and_b32_e32 v7, 0xffff0000, v179
	v_pk_mul_f32 v[6:7], v[6:7], v[6:7]
	s_nop 0
	v_add_f32_e32 v6, v6, v7
	v_add_f32_e32 v20, v6, v20
	v_lshlrev_b32_e32 v6, 16, v172
	v_and_b32_e32 v7, 0xffff0000, v172
	v_pk_mul_f32 v[6:7], v[6:7], v[6:7]
	s_nop 0
	v_add_f32_e32 v6, v6, v7
	v_add_f32_e32 v22, v20, v6
	v_and_b32_e32 v20, 0xffff0000, v173
	v_lshlrev_b32_e32 v7, 16, v174
	v_lshlrev_b32_e32 v6, 16, v173
	v_pk_mul_f32 v[16:17], v[20:21], v[20:21]
	s_nop 0
	v_pk_fma_f32 v[6:7], v[6:7], v[6:7], v[16:17]
	v_and_b32_e32 v17, 0xffff0000, v170
	v_add_f32_e32 v6, v6, v22
	v_add_f32_e32 v16, v7, v6
	v_lshlrev_b32_e32 v6, 16, v175
	v_and_b32_e32 v7, 0xffff0000, v175
	v_pk_mul_f32 v[6:7], v[6:7], v[6:7]
	s_nop 0
	v_add_f32_e32 v6, v6, v7
	v_add_f32_e32 v16, v6, v16
	v_lshlrev_b32_e32 v6, 16, v168
	v_and_b32_e32 v7, 0xffff0000, v168
	v_pk_mul_f32 v[6:7], v[6:7], v[6:7]
	s_nop 0
	v_add_f32_e32 v6, v6, v7
	v_add_f32_e32 v18, v16, v6
	v_and_b32_e32 v16, 0xffff0000, v169
	v_lshlrev_b32_e32 v7, 16, v170
	v_lshlrev_b32_e32 v6, 16, v169
	v_pk_mul_f32 v[12:13], v[16:17], v[16:17]
	s_nop 0
	v_pk_fma_f32 v[6:7], v[6:7], v[6:7], v[12:13]
	v_and_b32_e32 v13, 0xffff0000, v166
	v_add_f32_e32 v6, v6, v18
	v_add_f32_e32 v12, v7, v6
	v_lshlrev_b32_e32 v6, 16, v171
	v_and_b32_e32 v7, 0xffff0000, v171
	v_pk_mul_f32 v[6:7], v[6:7], v[6:7]
	s_nop 0
	v_add_f32_e32 v6, v6, v7
	v_add_f32_e32 v12, v6, v12
	v_lshlrev_b32_e32 v6, 16, v164
	v_and_b32_e32 v7, 0xffff0000, v164
	v_pk_mul_f32 v[6:7], v[6:7], v[6:7]
	s_nop 0
	v_add_f32_e32 v6, v6, v7
	v_add_f32_e32 v14, v12, v6
	v_and_b32_e32 v12, 0xffff0000, v165
	v_lshlrev_b32_e32 v7, 16, v166
	v_lshlrev_b32_e32 v6, 16, v165
	v_pk_mul_f32 v[8:9], v[12:13], v[12:13]
	s_nop 0
	v_pk_fma_f32 v[6:7], v[6:7], v[6:7], v[8:9]
	s_nop 0
	v_add_f32_e32 v6, v6, v14
	v_add_f32_e32 v8, v7, v6
	v_lshlrev_b32_e32 v6, 16, v167
	v_and_b32_e32 v7, 0xffff0000, v167
	v_pk_mul_f32 v[6:7], v[6:7], v[6:7]
	s_nop 0
	v_add_f32_e32 v6, v6, v7
	v_add_f32_e32 v6, v6, v8
	v_lshl_add_u64 v[2:3], v[180:181], 0, 64
	v_lshlrev_b32_e32 v24, 16, v200
	v_and_b32_e32 v25, 0xffff0000, v200
	v_pk_mul_f32 v[24:25], v[24:25], v[24:25]
	s_nop 0
	v_add_f32_e32 v7, v24, v25
	v_and_b32_e32 v25, 0xffff0000, v202
	v_and_b32_e32 v24, 0xffff0000, v201
	v_add_f32_e32 v26, v6, v7
	v_lshlrev_b32_e32 v7, 16, v202
	v_lshlrev_b32_e32 v6, 16, v201
	v_pk_mul_f32 v[20:21], v[24:25], v[24:25]
	s_nop 0
	v_pk_fma_f32 v[6:7], v[6:7], v[6:7], v[20:21]
	v_and_b32_e32 v21, 0xffff0000, v194
	v_add_f32_e32 v6, v6, v26
	v_add_f32_e32 v20, v7, v6
	v_lshlrev_b32_e32 v6, 16, v203
	v_and_b32_e32 v7, 0xffff0000, v203
	v_pk_mul_f32 v[6:7], v[6:7], v[6:7]
	s_nop 0
	v_add_f32_e32 v6, v6, v7
	v_add_f32_e32 v20, v6, v20
	v_lshlrev_b32_e32 v6, 16, v192
	v_and_b32_e32 v7, 0xffff0000, v192
	v_pk_mul_f32 v[6:7], v[6:7], v[6:7]
	s_nop 0
	v_add_f32_e32 v6, v6, v7
	v_add_f32_e32 v22, v20, v6
	v_and_b32_e32 v20, 0xffff0000, v193
	v_lshlrev_b32_e32 v7, 16, v194
	v_lshlrev_b32_e32 v6, 16, v193
	v_pk_mul_f32 v[16:17], v[20:21], v[20:21]
	s_nop 0
	v_pk_fma_f32 v[6:7], v[6:7], v[6:7], v[16:17]
	v_and_b32_e32 v17, 0xffff0000, v190
	v_add_f32_e32 v6, v6, v22
	v_add_f32_e32 v16, v7, v6
	v_lshlrev_b32_e32 v6, 16, v195
	v_and_b32_e32 v7, 0xffff0000, v195
	v_pk_mul_f32 v[6:7], v[6:7], v[6:7]
	s_nop 0
	v_add_f32_e32 v6, v6, v7
	v_add_f32_e32 v16, v6, v16
	v_lshlrev_b32_e32 v6, 16, v188
	v_and_b32_e32 v7, 0xffff0000, v188
	v_pk_mul_f32 v[6:7], v[6:7], v[6:7]
	s_nop 0
	v_add_f32_e32 v6, v6, v7
	v_add_f32_e32 v18, v16, v6
	v_and_b32_e32 v16, 0xffff0000, v189
	v_lshlrev_b32_e32 v7, 16, v190
	v_lshlrev_b32_e32 v6, 16, v189
	v_pk_mul_f32 v[12:13], v[16:17], v[16:17]
	s_nop 0
	v_pk_fma_f32 v[6:7], v[6:7], v[6:7], v[12:13]
	v_and_b32_e32 v13, 0xffff0000, v186
	v_add_f32_e32 v6, v6, v18
	v_add_f32_e32 v12, v7, v6
	v_lshlrev_b32_e32 v6, 16, v191
	v_and_b32_e32 v7, 0xffff0000, v191
	v_pk_mul_f32 v[6:7], v[6:7], v[6:7]
	s_nop 0
	v_add_f32_e32 v6, v6, v7
	v_add_f32_e32 v12, v6, v12
	v_lshlrev_b32_e32 v6, 16, v184
	v_and_b32_e32 v7, 0xffff0000, v184
	v_pk_mul_f32 v[6:7], v[6:7], v[6:7]
	s_nop 0
	v_add_f32_e32 v6, v6, v7
	v_add_f32_e32 v14, v12, v6
	v_and_b32_e32 v12, 0xffff0000, v185
	v_lshlrev_b32_e32 v7, 16, v186
	v_lshlrev_b32_e32 v6, 16, v185
	v_pk_mul_f32 v[8:9], v[12:13], v[12:13]
	s_nop 0
	v_pk_fma_f32 v[6:7], v[6:7], v[6:7], v[8:9]
	s_nop 0
	v_add_f32_e32 v6, v6, v14
	v_add_f32_e32 v8, v7, v6
	v_lshlrev_b32_e32 v6, 16, v187
	v_and_b32_e32 v7, 0xffff0000, v187
	v_pk_mul_f32 v[6:7], v[6:7], v[6:7]
	s_nop 0
	v_add_f32_e32 v6, v6, v7
	v_add_f32_e32 v6, v6, v8
	v_and_b32_e32 v3, 64, v219
	v_xor_b32_e32 v2, 1, v219
	v_add_u32_e32 v87, 64, v3
	v_cmp_lt_i32_e32 vcc, v2, v87
	s_nop 1
	v_cndmask_b32_e32 v2, v219, v2, vcc
	v_lshlrev_b32_e32 v2, 2, v2
	ds_bpermute_b32 v2, v2, v6
	v_cmp_eq_u32_e32 vcc, 0, v5
	s_and_saveexec_b64 s[8:9], vcc
	s_cbranch_execz .LBB0_735
	s_waitcnt lgkmcnt(0)
	v_add_f32_e32 v2, v6, v2
	s_mov_b32 s2, 0x43c00000
	v_div_scale_f32 v3, s[10:11], s2, s2, v2
	v_rcp_f32_e32 v5, v3
	v_div_scale_f32 v6, vcc, v2, s2, v2
	v_fma_f32 v7, -v3, v5, 1.0
	v_fmac_f32_e32 v5, v7, v5
	v_mul_f32_e32 v7, v6, v5
	v_fma_f32 v8, -v3, v7, v6
	v_fmac_f32_e32 v7, v8, v5
	v_fma_f32 v3, -v3, v7, v6
	v_div_fmas_f32 v3, v3, v5, v7
	v_div_fixup_f32 v2, v3, s2, v2
	v_add_f32_e32 v2, 0x358637bd, v2
	s_mov_b32 s2, 0x800000
	v_mul_f32_e32 v3, 0x4b800000, v2
	v_cmp_gt_f32_e32 vcc, s2, v2
	s_nop 1
	v_cndmask_b32_e32 v2, v2, v3, vcc
	v_rsq_f32_e32 v2, v2
	s_nop 0
	v_mul_f32_e32 v3, 0x45800000, v2
	v_cndmask_b32_e32 v2, v2, v3, vcc
	v_lshl_add_u32 v3, v4, 2, v234
	ds_write_b32 v3, v2

; DI int tidx() { int t = __builtin_amdgcn_workitem_id_x(); asm volatile("" : "+v"(t)); return t; }
; DI void final_norm(KP p, int u) {
;   const int lane = tidx() & 63, w = tidx() >> 6;
;   const int row = u * 4 + w;
;   float* xr = p->out + (size_t)row * 1024;
;   f32x4 v[4];
;   float ss = 0;
; #pragma unroll
;   for (int j = 0; j < 4; ++j) {
;     v[j] = *(const f32x4*)(xr + 4 * (lane + 64 * j));
;     ss += v[j].x * v[j].x + v[j].y * v[j].y + v[j].z * v[j].z + v[j].w * v[j].w;
;   }
;   ss = wave_sum(ss);
;   const float rstd = rsqrtf(ss * (1.f / 1024.f) + EPS);
; #pragma unroll
;   for (int j = 0; j < 4; ++j) {
;     const int c0 = 4 * (lane + 64 * j);
;     f32x4 gg = *(const f32x4*)(p->final_norm_g + c0);
;     *(f32x4*)(xr + c0) = mkf4(v[j].x * rstd * gg.x, v[j].y * rstd * gg.y, v[j].z * rstd * gg.z, v[j].w * rstd * gg.w);
;   }
; }
.LBB0_2074:
	s_mov_b64 s[8:9], s[0:1]
	v_mov_b32_e32 v2, v0
	v_mov_b32_e32 v11, v0
	s_load_dwordx4 s[4:7], s[8:9], 0x120
	v_ashrrev_i32_e32 v11, 6, v11
	v_add_u32_e32 v12, s3, v11
	v_ashrrev_i32_e32 v13, 31, v12
	v_lshlrev_b32_e32 v2, 4, v2
	v_lshlrev_b64 v[12:13], 12, v[12:13]
	v_and_b32_e32 v2, 0x3f0, v2
	s_waitcnt lgkmcnt(0)
	v_lshl_add_u64 v[12:13], s[6:7], 0, v[12:13]
	v_lshl_add_u64 v[32:33], v[12:13], 0, v[2:3]
	global_load_dwordx4 v[12:15], v[32:33], off
	global_load_dwordx4 v[16:19], v[32:33], off offset:1024
	global_load_dwordx4 v[20:23], v[32:33], off offset:2048
	global_load_dwordx4 v[24:27], v[32:33], off offset:3072
	global_load_dwordx4 v[132:135], v2, s[4:5]
	global_load_dwordx4 v[136:139], v2, s[4:5] offset:1024
	global_load_dwordx4 v[140:143], v2, s[4:5] offset:2048
	global_load_dwordx4 v[144:147], v2, s[4:5] offset:3072
	s_waitcnt vmcnt(0)
	v_cmp_lt_i32_e32 vcc, v4, v1
	s_add_i32 s72, s72, s61
	s_add_i32 s3, s3, s20
	v_cndmask_b32_e32 v11, v219, v4, vcc
	v_cmp_lt_i32_e32 vcc, v5, v1
	v_lshlrev_b32_e32 v11, 2, v11
	s_cmpk_gt_i32 s72, 0xfff
	v_cndmask_b32_e32 v28, v219, v5, vcc
	v_cmp_lt_i32_e32 vcc, v6, v1
	v_lshlrev_b32_e32 v50, 2, v28
	v_mov_b32_e32 v36, v13
	v_cndmask_b32_e32 v29, v219, v6, vcc
	v_cmp_lt_i32_e32 vcc, v7, v1
	v_lshlrev_b32_e32 v51, 2, v29
	v_mov_b32_e32 v37, v17
	v_cndmask_b32_e32 v30, v219, v7, vcc
	v_cmp_lt_i32_e32 vcc, v8, v1
	v_lshlrev_b32_e32 v52, 2, v30
	v_mov_b32_e32 v35, v16
	v_cndmask_b32_e32 v31, v219, v8, vcc
	v_lshlrev_b32_e32 v53, 2, v31
	v_cmp_lt_i32_e32 vcc, v9, v1
	v_mov_b32_e32 v44, v21
	v_mov_b32_e32 v45, v25
	v_cndmask_b32_e32 v34, v219, v9, vcc
	v_lshlrev_b32_e32 v54, 2, v34
	v_mov_b32_e32 v34, v12
	v_pk_mul_f32 v[36:37], v[36:37], v[36:37]
	v_mov_b32_e32 v38, v14
	v_mov_b32_e32 v39, v18
	v_mov_b32_e32 v42, v20
	v_mov_b32_e32 v43, v24
	v_pk_mul_f32 v[44:45], v[44:45], v[44:45]
	v_pk_fma_f32 v[34:35], v[34:35], v[34:35], v[36:37]
	v_mov_b32_e32 v40, v15
	v_mov_b32_e32 v41, v19
	v_mov_b32_e32 v46, v22
	v_mov_b32_e32 v47, v26
	v_pk_fma_f32 v[36:37], v[42:43], v[42:43], v[44:45]
	v_pk_fma_f32 v[34:35], v[38:39], v[38:39], v[34:35]
	v_mov_b32_e32 v48, v23
	v_mov_b32_e32 v49, v27
	v_pk_fma_f32 v[36:37], v[46:47], v[46:47], v[36:37]
	v_pk_fma_f32 v[34:35], v[40:41], v[40:41], v[34:35]
	v_pk_fma_f32 v[36:37], v[48:49], v[48:49], v[36:37]
	v_add_f32_e32 v34, v34, v35
	v_add_f32_e32 v34, v34, v36
	v_add_f32_e32 v34, v34, v37
	ds_bpermute_b32 v11, v11, v34
	s_waitcnt lgkmcnt(0)
	v_add_f32_e32 v11, v34, v11
	ds_bpermute_b32 v34, v50, v11
	s_waitcnt lgkmcnt(0)
	v_add_f32_e32 v11, v11, v34
	ds_bpermute_b32 v34, v51, v11
	s_waitcnt lgkmcnt(0)
	v_add_f32_e32 v11, v11, v34
	ds_bpermute_b32 v34, v52, v11
	s_waitcnt lgkmcnt(0)
	v_add_f32_e32 v11, v11, v34
	ds_bpermute_b32 v34, v53, v11
	s_waitcnt lgkmcnt(0)
	v_add_f32_e32 v11, v11, v34
	ds_bpermute_b32 v34, v54, v11
	s_waitcnt lgkmcnt(0)
	v_add_f32_e32 v11, v11, v34
	v_fmamk_f32 v11, v11, 0x3a800000, v10
	v_mul_f32_e32 v34, 0x4b800000, v11
	v_cmp_gt_f32_e32 vcc, s2, v11
	s_nop 1
	v_cndmask_b32_e32 v11, v11, v34, vcc
	v_rsq_f32_e32 v11, v11
	s_nop 0
	v_mul_f32_e32 v34, 0x45800000, v11
	v_cndmask_b32_e32 v34, v11, v34, vcc
	v_pk_mul_f32 v[12:13], v[12:13], v[34:35] op_sel_hi:[1,0]
	v_pk_mul_f32 v[14:15], v[14:15], v[34:35] op_sel_hi:[1,0]
	v_pk_mul_f32 v[18:19], v[18:19], v[34:35] op_sel_hi:[1,0]
	v_pk_mul_f32 v[16:17], v[16:17], v[34:35] op_sel_hi:[1,0]
	v_pk_mul_f32 v[14:15], v[134:135], v[14:15]
	v_pk_mul_f32 v[12:13], v[132:133], v[12:13]
	global_store_dwordx4 v[32:33], v[12:15], off
	s_nop 1
	v_pk_mul_f32 v[12:13], v[136:137], v[16:17]
	v_pk_mul_f32 v[14:15], v[138:139], v[18:19]
	global_store_dwordx4 v[32:33], v[12:15], off offset:1024
	s_nop 1
	v_pk_mul_f32 v[16:17], v[22:23], v[34:35] op_sel_hi:[1,0]
	v_pk_mul_f32 v[18:19], v[20:21], v[34:35] op_sel_hi:[1,0]
	v_pk_mul_f32 v[14:15], v[142:143], v[16:17]
	v_pk_mul_f32 v[12:13], v[140:141], v[18:19]
	global_store_dwordx4 v[32:33], v[12:15], off offset:2048
	s_nop 1
	v_pk_mul_f32 v[16:17], v[26:27], v[34:35] op_sel_hi:[1,0]
	v_pk_mul_f32 v[18:19], v[24:25], v[34:35] op_sel_hi:[1,0]
	v_pk_mul_f32 v[14:15], v[146:147], v[16:17]
	v_pk_mul_f32 v[12:13], v[144:145], v[18:19]
	global_store_dwordx4 v[32:33], v[12:15], off offset:3072
	s_cbranch_scc0 .LBB0_2074
